# SSD1 chunk-state stores widened: lane pairs exchange halves with ds_swizzle (SWAP,16) and write 16 dwordx4 per unit instead of 32 dwordx2; on top of the P0b scale-load hoist
# baseline (speedup 1.0000x reference)
; #define LAS __attribute__((address_space(3)))
; __device__ __forceinline__ int otid() { int t = threadIdx.x; asm volatile("" : "+v"(t)); return t; }
; __device__ __forceinline__ float softplusf_(float x) { return fmaxf(x, 0.f) + log1pf(__expf(-fabsf(x))); }
; __device__ __forceinline__ void ssd_dt(const Params& p, LAS unsigned char* lds, int b, int c, int g) {
;     const int lane = otid() & 63, e = otid() >> 6, eg = 8 * g + e;
;     const float* SM = (const float*)(p.ws + WS_SM);
;     const float dt = softplusf_(SM[((size_t)b * SEQ + 64 * c + lane) * 256 + eg] + p.in[I_DTB][eg]);
;     float a = dt * -__expf(p.in[I_ALOG][eg]);
; #pragma unroll
;     for (int o = 1; o < 64; o <<= 1) { const float t = __shfl_up(a, o); if (lane >= o) a += t; }
;     ((LAS float*)(lds + SSD_ACS))[lane * 8 + e] = a; ((LAS float*)(lds + SSD_DT))[lane * 8 + e] = dt;
; }
.LBB0_566:
	s_or_b64 exec, exec, s[20:21]
	v_mov_b32_e32 v2, v194
	v_mov_b32_e32 v3, v194
	s_lshl_b32 s2, s34, 3
	v_and_b32_e32 v2, 63, v2
	v_ashrrev_i32_e32 v3, 6, v3
	v_add_u32_e32 v6, s2, v3
	v_or3_b32 v0, v0, v4, v2
	v_readlane_b32 s4, v253, 45
	v_ashrrev_i32_e32 v7, 31, v6
	v_lshlrev_b64 v[0:1], 10, v[0:1]
	v_readlane_b32 s5, v253, 46
	v_readlane_b32 s44, v253, 4
	v_readlane_b32 s54, v253, 14
	v_lshl_add_u64 v[4:5], s[4:5], 0, v[0:1]
	v_lshlrev_b64 v[0:1], 2, v[6:7]
	v_readlane_b32 s55, v253, 15
	v_lshl_add_u64 v[4:5], v[4:5], 0, v[0:1]
	global_load_dword v4, v[4:5], off
	v_lshl_add_u64 v[6:7], s[54:55], 0, v[0:1]
	global_load_dword v5, v[6:7], off
	v_readlane_b32 s56, v253, 16
	v_readlane_b32 s57, v253, 17
	s_mov_b32 s3, 0xbfb8aa3b
	v_add_u32_e32 v6, -1, v175
	v_lshl_add_u64 v[0:1], s[56:57], 0, v[0:1]
	global_load_dword v1, v[0:1], off
	v_and_b32_e32 v0, 64, v175
	s_mov_b32 s4, 0x3f2aaaab
	v_cmp_lt_i32_e32 vcc, v6, v0
	v_add_u32_e32 v7, -2, v175
	v_lshl_add_u32 v3, v2, 3, v3
	v_cndmask_b32_e32 v6, v6, v175, vcc
	v_lshlrev_b32_e32 v6, 2, v6
	v_lshl_add_u32 v3, v3, 2, 0
	s_lshl_b32 s6, s6, 5
	v_readlane_b32 s45, v253, 5
	v_readlane_b32 s46, v253, 6
	v_readlane_b32 s47, v253, 7
	v_readlane_b32 s48, v253, 8
	v_readlane_b32 s49, v253, 9
	v_readlane_b32 s50, v253, 10
	v_readlane_b32 s51, v253, 11
	v_readlane_b32 s52, v253, 12
	v_readlane_b32 s53, v253, 13
	v_readlane_b32 s58, v253, 18
	v_readlane_b32 s59, v253, 19
	s_waitcnt vmcnt(1)
	v_add_f32_e32 v4, v4, v5
	v_mul_f32_e64 v5, |v4|, s3
	v_exp_f32_e32 v8, v5
	v_max_f32_e32 v9, 0, v4
	s_waitcnt vmcnt(0)
	v_mul_f32_e32 v1, 0x3fb8aa3b, v1
	v_exp_f32_e32 v10, v1
	v_add_f32_e32 v1, 1.0, v8
	v_add_f32_e32 v11, -1.0, v1
	v_frexp_mant_f32_e32 v12, v1
	v_cvt_f64_f32_e32 v[4:5], v1
	v_sub_f32_e32 v13, v11, v1
	v_frexp_exp_i32_f64_e32 v4, v[4:5]
	v_cmp_gt_f32_e32 vcc, s4, v12
	v_sub_f32_e32 v11, v8, v11
	v_add_f32_e32 v5, 1.0, v13
	v_subbrev_co_u32_e32 v4, vcc, 0, v4, vcc
	v_add_f32_e32 v5, v11, v5
	v_sub_u32_e32 v11, 0, v4
	v_cvt_f32_i32_e32 v4, v4
	v_ldexp_f32 v1, v1, v11
	v_ldexp_f32 v5, v5, v11
	v_add_f32_e32 v11, -1.0, v1
	v_add_f32_e32 v12, 1.0, v1
	v_add_f32_e32 v13, 1.0, v11
	v_add_f32_e32 v14, -1.0, v12
	v_sub_f32_e32 v13, v1, v13
	v_sub_f32_e32 v1, v1, v14
	v_mul_f32_e32 v14, 0x3f317218, v4
	v_add_f32_e32 v13, v5, v13
	v_add_f32_e32 v1, v5, v1
	v_fma_f32 v5, v4, s28, -v14
	v_add_f32_e32 v15, v11, v13
	v_add_f32_e32 v16, v12, v1
	v_fmac_f32_e32 v5, 0xb102e308, v4
	v_sub_f32_e32 v4, v15, v11
	v_sub_f32_e32 v11, v16, v12
	v_rcp_f32_e32 v12, v16
	v_add_f32_e32 v17, v14, v5
	v_sub_f32_e32 v1, v1, v11
	v_sub_f32_e32 v11, v17, v14
	v_sub_f32_e32 v5, v5, v11
	v_mul_f32_e32 v11, v15, v12
	v_sub_f32_e32 v4, v13, v4
	v_mul_f32_e32 v13, v16, v11
	v_fma_f32 v14, v11, v16, -v13
	v_fmac_f32_e32 v14, v11, v1
	v_add_f32_e32 v18, v13, v14
	v_sub_f32_e32 v19, v15, v18
	v_sub_f32_e32 v13, v18, v13
	v_sub_f32_e32 v15, v15, v19
	v_sub_f32_e32 v13, v13, v14
	v_sub_f32_e32 v14, v15, v18
	v_add_f32_e32 v4, v4, v14
	v_add_f32_e32 v4, v13, v4
	v_add_f32_e32 v13, v19, v4
	v_mul_f32_e32 v14, v12, v13
	v_sub_f32_e32 v15, v19, v13
	v_mul_f32_e32 v18, v16, v14
	v_add_f32_e32 v4, v4, v15
	v_add_f32_e32 v15, v11, v14
	v_fma_f32 v16, v14, v16, -v18
	v_sub_f32_e32 v11, v15, v11
	v_fmac_f32_e32 v16, v14, v1
	v_sub_f32_e32 v1, v14, v11
	v_add_f32_e32 v11, v18, v16
	v_sub_f32_e32 v14, v11, v18
	v_sub_f32_e32 v18, v13, v11
	v_sub_f32_e32 v13, v13, v18
	v_sub_f32_e32 v11, v13, v11
	v_sub_f32_e32 v14, v14, v16
	v_add_f32_e32 v4, v4, v11
	v_add_f32_e32 v4, v14, v4
	v_add_f32_e32 v4, v18, v4
	v_mul_f32_e32 v4, v12, v4
	v_add_f32_e32 v1, v1, v4
	v_add_f32_e32 v4, v15, v1
	v_mul_f32_e32 v11, v4, v4
	v_fmamk_f32 v14, v11, 0x3e9b6dac, v174
	v_sub_f32_e32 v12, v4, v15
	v_ldexp_f32 v13, v4, 1
	v_mul_f32_e32 v4, v4, v11
	v_fmaak_f32 v11, v11, v14, 0x3f2aaada
	v_mul_f32_e32 v4, v4, v11
	v_add_f32_e32 v11, v13, v4
	v_sub_f32_e32 v1, v1, v12
	v_sub_f32_e32 v12, v11, v13
	v_ldexp_f32 v1, v1, 1
	v_sub_f32_e32 v4, v4, v12
	v_add_f32_e32 v1, v1, v4
	v_add_f32_e32 v4, v11, v1
	v_sub_f32_e32 v11, v4, v11
	v_add_f32_e32 v12, v17, v4
	v_sub_f32_e32 v1, v1, v11
	v_sub_f32_e32 v11, v12, v17
	v_sub_f32_e32 v13, v12, v11
	v_sub_f32_e32 v4, v4, v11
	v_add_f32_e32 v11, v5, v1
	v_sub_f32_e32 v13, v17, v13
	v_sub_f32_e32 v14, v11, v5
	v_add_f32_e32 v4, v4, v13
	v_sub_f32_e32 v13, v11, v14
	v_sub_f32_e32 v1, v1, v14
	v_sub_f32_e32 v5, v5, v13
	v_add_f32_e32 v4, v11, v4
	v_add_f32_e32 v1, v1, v5
	v_add_f32_e32 v5, v12, v4
	v_sub_f32_e32 v11, v5, v12
	v_sub_f32_e32 v4, v4, v11
	v_add_f32_e32 v1, v1, v4
	v_add_f32_e32 v1, v5, v1
	v_cmp_neq_f32_e32 vcc, s29, v8
	s_nop 1
	v_cndmask_b32_e32 v1, v180, v1, vcc
	v_cmp_ngt_f32_e32 vcc, -1.0, v8
	s_nop 1
	v_cndmask_b32_e32 v1, v181, v1, vcc
	v_cmp_neq_f32_e32 vcc, -1.0, v8
	s_nop 1
	v_cndmask_b32_e32 v1, v182, v1, vcc
	v_cmp_lt_f32_e64 vcc, |v8|, s30
	s_nop 1
	v_cndmask_b32_e32 v1, v1, v8, vcc
	v_add_f32_e32 v1, v9, v1
	v_mul_f32_e64 v4, v1, -v10
	ds_bpermute_b32 v5, v6, v4
	v_cmp_lt_i32_e32 vcc, v7, v0
	v_add_u32_e32 v6, -4, v175
	s_waitcnt lgkmcnt(0)
	v_fma_f32 v5, v1, -v10, v5
	v_cndmask_b32_e32 v7, v7, v175, vcc
	v_cmp_eq_u32_e32 vcc, 0, v2
	v_lshlrev_b32_e32 v7, 2, v7
	s_nop 0
	v_cndmask_b32_e32 v4, v5, v4, vcc
	ds_bpermute_b32 v5, v7, v4
	v_cmp_lt_i32_e32 vcc, v6, v0
	v_add_u32_e32 v7, -8, v175
	s_waitcnt lgkmcnt(0)
	v_add_f32_e32 v5, v4, v5
	v_cndmask_b32_e32 v6, v6, v175, vcc
	v_cmp_gt_u32_e32 vcc, 2, v2
	v_lshlrev_b32_e32 v6, 2, v6
	s_nop 0
	v_cndmask_b32_e32 v4, v5, v4, vcc
	ds_bpermute_b32 v5, v6, v4
	v_cmp_lt_i32_e32 vcc, v7, v0
	v_add_u32_e32 v6, -16, v175
	s_waitcnt lgkmcnt(0)
	v_add_f32_e32 v5, v4, v5
	v_cndmask_b32_e32 v7, v7, v175, vcc
	v_cmp_gt_u32_e32 vcc, 4, v2
	v_lshlrev_b32_e32 v7, 2, v7
	s_nop 0
	v_cndmask_b32_e32 v4, v5, v4, vcc
	ds_bpermute_b32 v5, v7, v4
	v_cmp_lt_i32_e32 vcc, v6, v0
	v_subrev_u32_e32 v7, 32, v175
	s_waitcnt lgkmcnt(0)
	v_add_f32_e32 v5, v4, v5
	v_cndmask_b32_e32 v6, v6, v175, vcc
	v_cmp_gt_u32_e32 vcc, 8, v2
	v_lshlrev_b32_e32 v6, 2, v6
	s_nop 0
	v_cndmask_b32_e32 v4, v5, v4, vcc
	ds_bpermute_b32 v5, v6, v4
	v_cmp_lt_i32_e32 vcc, v7, v0
	s_waitcnt lgkmcnt(0)
	v_add_f32_e32 v5, v4, v5
	v_cndmask_b32_e32 v0, v7, v175, vcc
	v_cmp_gt_u32_e32 vcc, 16, v2
	v_lshlrev_b32_e32 v0, 2, v0
	s_nop 0
	v_cndmask_b32_e32 v4, v5, v4, vcc
	ds_bpermute_b32 v0, v0, v4
	v_cmp_gt_u32_e32 vcc, 32, v2
	v_add_u32_e32 v5, 0x1f000, v3
	v_add_u32_e32 v3, 0x1f800, v3
	ds_write_b32 v3, v1
	s_waitcnt lgkmcnt(1)
	v_add_f32_e32 v0, v4, v0
	v_cndmask_b32_e32 v0, v0, v4, vcc
	ds_write_b32 v5, v0
	s_waitcnt lgkmcnt(0)
	s_barrier
; #define LAS __attribute__((address_space(3)))
; __device__ __forceinline__ unsigned cvt_pk_bf16(float lo, float hi) { unsigned r; asm volatile("v_cvt_pk_bf16_f32 %0, %1, %2" : "=v"(r) : "v"(lo), "v"(hi)); return r; }
; __device__ void phase_ssd1(const Params& p, LAS unsigned char* lds, int wg, int nwg) {
;     ...
;         LAS const float* ACS = (LAS const float*)(lds + SSD_ACS); LAS const float* DT = (LAS const float*)(lds + SSD_DT);
;         const float alast = ACS[63 * 8 + e];
;         f32x4 acc[8][4];
; #pragma unroll
;         for (int nt = 0; nt < 8; ++nt)
; #pragma unroll
;             for (int pt = 0; pt < 4; ++pt) acc[nt][pt] = (f32x4){0.f, 0.f, 0.f, 0.f};
; #pragma unroll
;         for (int ks = 0; ks < 2; ++ks) {
;             float wl[8];
; #pragma unroll
;             for (int j = 0; j < 8; ++j) { const int s = 32 * ks + 8 * fq + j; wl[j] = DT[s * 8 + e] * __expf(alast - ACS[s * 8 + e]); }
;             bf16x8 xb[4];
; #pragma unroll
;             for (int pt = 0; pt < 4; ++pt) {
;                 float f[8]; unpack8(*(LAS const u32x4*)(lds + SSD_XT + ((64 * e + 16 * pt + fr) * 72 + 32 * ks + 8 * fq) * 2), f);
;                 u32x4 w; w.x = pg8::cvt_pk_bf16(f[0] * wl[0], f[1] * wl[1]); w.y = pg8::cvt_pk_bf16(f[2] * wl[2], f[3] * wl[3]); w.z = pg8::cvt_pk_bf16(f[4] * wl[4], f[5] * wl[5]); w.w = pg8::cvt_pk_bf16(f[6] * wl[6], f[7] * wl[7]);
;                 xb[pt] = __builtin_bit_cast(bf16x8, w);
;             }
; #pragma unroll
;             for (int nt = 0; nt < 8; ++nt) {
;                 const bf16x8 bt = *(LAS const bf16x8*)(lds + SSD_B + ((16 * nt + fr) * 72 + 32 * ks + 8 * fq) * 2);
; #pragma unroll
;                 for (int pt = 0; pt < 4; ++pt) acc[nt][pt] = __builtin_amdgcn_mfma_f32_16x16x32_bf16(bt, xb[pt], acc[nt][pt], 0, 0, 0);
	ds_read_b32 v183, v141 offset:2016
	ds_read_b32 v0, v142
	ds_read_b32 v1, v143
	ds_read_b32 v2, v144
	ds_read_b32 v3, v145
	ds_read_b32 v4, v146
	ds_read_b32 v5, v147
	ds_read_b32 v6, v148
	s_waitcnt lgkmcnt(5)
	v_sub_f32_e32 v1, v183, v1
	v_mul_f32_e32 v1, 0x3fb8aa3b, v1
	ds_read_b32 v7, v149
	ds_read_b32 v8, v150
	ds_read_b32 v9, v151
	ds_read_b32 v10, v152
	ds_read_b32 v11, v153
	ds_read_b32 v12, v154
	ds_read_b32 v13, v155
	ds_read_b32 v14, v156
	v_exp_f32_e32 v1, v1
	s_waitcnt lgkmcnt(9)
	v_sub_f32_e32 v5, v183, v5
	s_waitcnt lgkmcnt(7)
	v_sub_f32_e32 v7, v183, v7
	v_mul_f32_e32 v5, 0x3fb8aa3b, v5
	v_mul_f32_e32 v7, 0x3fb8aa3b, v7
	v_exp_f32_e32 v5, v5
	v_exp_f32_e32 v7, v7
	v_sub_f32_e32 v3, v183, v3
	v_mul_f32_e32 v16, v0, v1
	s_waitcnt lgkmcnt(5)
	v_sub_f32_e32 v0, v183, v9
	v_mul_f32_e32 v3, 0x3fb8aa3b, v3
	v_mul_f32_e32 v0, 0x3fb8aa3b, v0
	v_exp_f32_e32 v3, v3
	v_mul_f32_e32 v18, v4, v5
	v_mul_f32_e32 v19, v6, v7
	v_exp_f32_e32 v4, v0
	s_waitcnt lgkmcnt(3)
	v_sub_f32_e32 v0, v183, v11
	ds_read_b32 v6, v157
	v_mul_f32_e32 v0, 0x3fb8aa3b, v0
	v_exp_f32_e32 v5, v0
	s_waitcnt lgkmcnt(2)
	v_sub_f32_e32 v0, v183, v13
	v_mul_f32_e32 v0, 0x3fb8aa3b, v0
	v_mul_f32_e32 v17, v2, v3
	v_exp_f32_e32 v7, v0
	ds_read_b128 v[0:3], v176
	s_waitcnt lgkmcnt(1)
	v_sub_f32_e32 v6, v183, v6
	v_mul_f32_e32 v6, 0x3fb8aa3b, v6
	v_exp_f32_e32 v6, v6
	v_mul_f32_e32 v20, v8, v4
	s_waitcnt lgkmcnt(0)
	v_lshlrev_b32_e32 v4, 16, v0
	v_and_b32_e32 v0, 0xffff0000, v0
	v_mul_f32_e32 v21, v10, v5
	v_lshlrev_b32_e32 v5, 16, v1
	v_and_b32_e32 v1, 0xffff0000, v1
	v_mul_f32_e32 v0, v17, v0
	v_mul_f32_e32 v22, v12, v7
	v_mul_f32_e32 v23, v14, v6
	v_lshlrev_b32_e32 v6, 16, v2
	v_and_b32_e32 v2, 0xffff0000, v2
	v_mul_f32_e32 v4, v16, v4
	v_cvt_pk_bf16_f32 v12, v4, v0
	v_mul_f32_e32 v0, v18, v5
	v_mul_f32_e32 v1, v19, v1
	v_lshlrev_b32_e32 v7, 16, v3
	v_and_b32_e32 v3, 0xffff0000, v3
	v_cvt_pk_bf16_f32 v13, v0, v1
	v_mul_f32_e32 v0, v20, v6
	v_mul_f32_e32 v1, v21, v2
	v_cvt_pk_bf16_f32 v14, v0, v1
	v_mul_f32_e32 v0, v22, v7
	v_mul_f32_e32 v1, v23, v3
	v_cvt_pk_bf16_f32 v15, v0, v1
	ds_read_b128 v[0:3], v176 offset:2304
	s_waitcnt lgkmcnt(0)
	v_lshlrev_b32_e32 v4, 16, v0
	v_and_b32_e32 v0, 0xffff0000, v0
	v_lshlrev_b32_e32 v5, 16, v1
	v_and_b32_e32 v1, 0xffff0000, v1
	v_mul_f32_e32 v0, v17, v0
	v_lshlrev_b32_e32 v6, 16, v2
	v_and_b32_e32 v2, 0xffff0000, v2
	v_mul_f32_e32 v4, v16, v4
	v_cvt_pk_bf16_f32 v8, v4, v0
	v_mul_f32_e32 v0, v18, v5
	v_mul_f32_e32 v1, v19, v1
	v_lshlrev_b32_e32 v7, 16, v3
	v_and_b32_e32 v3, 0xffff0000, v3
	v_cvt_pk_bf16_f32 v9, v0, v1
	v_mul_f32_e32 v0, v20, v6
	v_mul_f32_e32 v1, v21, v2
	v_cvt_pk_bf16_f32 v10, v0, v1
	v_mul_f32_e32 v0, v22, v7
	v_mul_f32_e32 v1, v23, v3
	v_cvt_pk_bf16_f32 v11, v0, v1
	ds_read_b128 v[0:3], v176 offset:4608
	s_waitcnt lgkmcnt(0)
	v_lshlrev_b32_e32 v4, 16, v0
	v_and_b32_e32 v0, 0xffff0000, v0
	v_lshlrev_b32_e32 v5, 16, v1
	v_and_b32_e32 v1, 0xffff0000, v1
	v_mul_f32_e32 v4, v16, v4
	v_mul_f32_e32 v0, v17, v0
	v_lshlrev_b32_e32 v6, 16, v2
	v_and_b32_e32 v2, 0xffff0000, v2
	v_cvt_pk_bf16_f32 v4, v4, v0
	v_mul_f32_e32 v0, v18, v5
	v_mul_f32_e32 v1, v19, v1
	v_lshlrev_b32_e32 v7, 16, v3
	v_and_b32_e32 v3, 0xffff0000, v3
	v_cvt_pk_bf16_f32 v5, v0, v1
	v_mul_f32_e32 v0, v20, v6
	v_mul_f32_e32 v1, v21, v2
	v_cvt_pk_bf16_f32 v6, v0, v1
	v_mul_f32_e32 v0, v22, v7
	v_mul_f32_e32 v1, v23, v3
	v_cvt_pk_bf16_f32 v7, v0, v1
	ds_read_b128 v[0:3], v176 offset:6912
	s_waitcnt lgkmcnt(0)
	v_lshlrev_b32_e32 v24, 16, v0
	v_and_b32_e32 v0, 0xffff0000, v0
	v_lshlrev_b32_e32 v25, 16, v1
	v_and_b32_e32 v1, 0xffff0000, v1
	v_mul_f32_e32 v16, v16, v24
	v_mul_f32_e32 v0, v17, v0
	v_lshlrev_b32_e32 v26, 16, v2
	v_and_b32_e32 v2, 0xffff0000, v2
	v_cvt_pk_bf16_f32 v0, v16, v0
	v_mul_f32_e32 v16, v18, v25
	v_mul_f32_e32 v1, v19, v1
	v_lshlrev_b32_e32 v27, 16, v3
	v_and_b32_e32 v3, 0xffff0000, v3
	v_cvt_pk_bf16_f32 v1, v16, v1
	v_mul_f32_e32 v16, v20, v26
	v_mul_f32_e32 v2, v21, v2
	v_cvt_pk_bf16_f32 v2, v16, v2
	v_mul_f32_e32 v16, v22, v27
	v_mul_f32_e32 v3, v23, v3
	v_cvt_pk_bf16_f32 v3, v16, v3
	ds_read_b128 v[16:19], v177
	ds_read_b128 v[132:135], v176 offset:64
	s_waitcnt lgkmcnt(1)
	v_mfma_f32_16x16x32_bf16 v[112:115], v[16:19], v[12:15], 0
	v_mfma_f32_16x16x32_bf16 v[116:119], v[16:19], v[8:11], 0
	v_mfma_f32_16x16x32_bf16 v[120:123], v[16:19], v[4:7], 0
	v_mfma_f32_16x16x32_bf16 v[124:127], v[16:19], v[0:3], 0
	ds_read_b128 v[16:19], v177 offset:2304
	ds_read_b128 v[20:23], v177 offset:4608
	s_waitcnt lgkmcnt(1)
	v_mfma_f32_16x16x32_bf16 v[96:99], v[16:19], v[12:15], 0
	v_mfma_f32_16x16x32_bf16 v[100:103], v[16:19], v[8:11], 0
	v_mfma_f32_16x16x32_bf16 v[104:107], v[16:19], v[4:7], 0
	v_mfma_f32_16x16x32_bf16 v[108:111], v[16:19], v[0:3], 0
	s_waitcnt lgkmcnt(0)
	v_mfma_f32_16x16x32_bf16 v[80:83], v[20:23], v[12:15], 0
	v_mfma_f32_16x16x32_bf16 v[84:87], v[20:23], v[8:11], 0
	v_mfma_f32_16x16x32_bf16 v[88:91], v[20:23], v[4:7], 0
	v_mfma_f32_16x16x32_bf16 v[92:95], v[20:23], v[0:3], 0
	ds_read_b128 v[16:19], v177 offset:6912
	ds_read_b128 v[20:23], v177 offset:9216
	s_waitcnt lgkmcnt(1)
	v_mfma_f32_16x16x32_bf16 v[64:67], v[16:19], v[12:15], 0
	v_mfma_f32_16x16x32_bf16 v[68:71], v[16:19], v[8:11], 0
	v_mfma_f32_16x16x32_bf16 v[72:75], v[16:19], v[4:7], 0
	v_mfma_f32_16x16x32_bf16 v[76:79], v[16:19], v[0:3], 0
	ds_read_b128 v[16:19], v177 offset:11520
	ds_read_b128 v[28:31], v177 offset:13824
	ds_read_b128 v[128:131], v177 offset:16128
	ds_read_b32 v184, v158
	ds_read_b32 v185, v159
	ds_read_b32 v186, v160
	ds_read_b32 v187, v161
	ds_read_b32 v188, v162
	ds_read_b32 v189, v163
	ds_read_b32 v190, v164
	ds_read_b32 v191, v165
	s_waitcnt lgkmcnt(6)
; #define LAS __attribute__((address_space(3)))
; __device__ __forceinline__ unsigned cvt_pk_bf16(float lo, float hi) { unsigned r; asm volatile("v_cvt_pk_bf16_f32 %0, %1, %2" : "=v"(r) : "v"(lo), "v"(hi)); return r; }
; __device__ void phase_ssd1(const Params& p, LAS unsigned char* lds, int wg, int nwg) {
;     ...
;         for (int ks = 0; ks < 2; ++ks) {
;             float wl[8];
; #pragma unroll
;             for (int j = 0; j < 8; ++j) { const int s = 32 * ks + 8 * fq + j; wl[j] = DT[s * 8 + e] * __expf(alast - ACS[s * 8 + e]); }
;             bf16x8 xb[4];
; #pragma unroll
;             for (int pt = 0; pt < 4; ++pt) {
;                 float f[8]; unpack8(*(LAS const u32x4*)(lds + SSD_XT + ((64 * e + 16 * pt + fr) * 72 + 32 * ks + 8 * fq) * 2), f);
;                 u32x4 w; w.x = pg8::cvt_pk_bf16(f[0] * wl[0], f[1] * wl[1]); w.y = pg8::cvt_pk_bf16(f[2] * wl[2], f[3] * wl[3]); w.z = pg8::cvt_pk_bf16(f[4] * wl[4], f[5] * wl[5]); w.w = pg8::cvt_pk_bf16(f[6] * wl[6], f[7] * wl[7]);
;                 xb[pt] = __builtin_bit_cast(bf16x8, w);
;             }
; #pragma unroll
;             for (int nt = 0; nt < 8; ++nt) {
;                 const bf16x8 bt = *(LAS const bf16x8*)(lds + SSD_B + ((16 * nt + fr) * 72 + 32 * ks + 8 * fq) * 2);
; #pragma unroll
;                 for (int pt = 0; pt < 4; ++pt) acc[nt][pt] = __builtin_amdgcn_mfma_f32_16x16x32_bf16(bt, xb[pt], acc[nt][pt], 0, 0, 0);
	v_sub_f32_e32 v185, v183, v185
	s_waitcnt lgkmcnt(4)
	v_sub_f32_e32 v187, v183, v187
	s_waitcnt lgkmcnt(2)
	v_sub_f32_e32 v189, v183, v189
	v_mul_f32_e32 v185, 0x3fb8aa3b, v185
	s_waitcnt lgkmcnt(0)
	v_sub_f32_e32 v191, v183, v191
	v_mul_f32_e32 v187, 0x3fb8aa3b, v187
	v_mul_f32_e32 v189, 0x3fb8aa3b, v189
	v_mul_f32_e32 v191, 0x3fb8aa3b, v191
	v_exp_f32_e32 v185, v185
	v_exp_f32_e32 v187, v187
	v_exp_f32_e32 v189, v189
	v_exp_f32_e32 v191, v191
	v_mul_f32_e32 v192, v184, v185
	v_mul_f32_e32 v193, v186, v187
	v_mul_f32_e32 v195, v188, v189
	v_mul_f32_e32 v200, v190, v191
	ds_read_b32 v184, v166
	ds_read_b32 v185, v167
	ds_read_b32 v186, v168
	ds_read_b32 v187, v169
	ds_read_b32 v188, v170
	ds_read_b32 v189, v171
	ds_read_b32 v190, v172
	ds_read_b32 v191, v173
	s_waitcnt lgkmcnt(6)
	v_sub_f32_e32 v185, v183, v185
	v_mul_f32_e32 v185, 0x3fb8aa3b, v185
	v_exp_f32_e32 v185, v185
	s_waitcnt lgkmcnt(4)
	v_sub_f32_e32 v187, v183, v187
	v_mul_f32_e32 v187, 0x3fb8aa3b, v187
	s_waitcnt lgkmcnt(2)
	v_sub_f32_e32 v189, v183, v189
	s_waitcnt lgkmcnt(0)
	v_sub_f32_e32 v191, v183, v191
	v_exp_f32_e32 v187, v187
	v_mul_f32_e32 v189, 0x3fb8aa3b, v189
	v_mul_f32_e32 v191, 0x3fb8aa3b, v191
	v_exp_f32_e32 v189, v189
	v_exp_f32_e32 v191, v191
	v_mul_f32_e32 v201, v184, v185
	v_lshlrev_b32_e32 v184, 16, v132
	v_and_b32_e32 v132, 0xffff0000, v132
	v_lshlrev_b32_e32 v185, 16, v133
	v_and_b32_e32 v133, 0xffff0000, v133
	v_mul_f32_e32 v184, v192, v184
	v_mul_f32_e32 v132, v193, v132
	v_mul_f32_e32 v202, v186, v187
	v_lshlrev_b32_e32 v186, 16, v134
	v_and_b32_e32 v134, 0xffff0000, v134
	v_cvt_pk_bf16_f32 v132, v184, v132
	v_mul_f32_e32 v184, v195, v185
	v_mul_f32_e32 v133, v200, v133
	v_mul_f32_e32 v203, v188, v189
	v_mul_f32_e32 v204, v190, v191
	v_lshlrev_b32_e32 v187, 16, v135
	v_and_b32_e32 v135, 0xffff0000, v135
	v_cvt_pk_bf16_f32 v133, v184, v133
	v_mul_f32_e32 v184, v201, v186
	v_mul_f32_e32 v134, v202, v134
	v_cvt_pk_bf16_f32 v134, v184, v134
	v_mul_f32_e32 v184, v203, v187
	v_mul_f32_e32 v135, v204, v135
	v_cvt_pk_bf16_f32 v135, v184, v135
	ds_read_b128 v[184:187], v176 offset:2368
	v_mfma_f32_16x16x32_bf16 v[48:51], v[20:23], v[12:15], 0
	s_waitcnt lgkmcnt(0)
	v_lshlrev_b32_e32 v188, 16, v184
	v_and_b32_e32 v184, 0xffff0000, v184
	v_lshlrev_b32_e32 v189, 16, v185
	v_and_b32_e32 v185, 0xffff0000, v185
	v_mul_f32_e32 v188, v192, v188
	v_mul_f32_e32 v184, v193, v184
	v_lshlrev_b32_e32 v190, 16, v186
	v_and_b32_e32 v186, 0xffff0000, v186
	v_cvt_pk_bf16_f32 v184, v188, v184
	v_mul_f32_e32 v188, v195, v189
	v_mul_f32_e32 v185, v200, v185
	v_lshlrev_b32_e32 v191, 16, v187
	v_and_b32_e32 v187, 0xffff0000, v187
	v_cvt_pk_bf16_f32 v185, v188, v185
	v_mul_f32_e32 v188, v201, v190
	v_mul_f32_e32 v186, v202, v186
	v_cvt_pk_bf16_f32 v186, v188, v186
	v_mul_f32_e32 v188, v203, v191
	v_mul_f32_e32 v187, v204, v187
	v_cvt_pk_bf16_f32 v187, v188, v187
	ds_read_b128 v[188:191], v176 offset:4672
	v_mfma_f32_16x16x32_bf16 v[52:55], v[20:23], v[8:11], 0
	s_waitcnt lgkmcnt(0)
	v_lshlrev_b32_e32 v196, 16, v188
	v_and_b32_e32 v188, 0xffff0000, v188
	v_lshlrev_b32_e32 v197, 16, v189
	v_and_b32_e32 v189, 0xffff0000, v189
	v_mul_f32_e32 v196, v192, v196
	v_mul_f32_e32 v188, v193, v188
	v_lshlrev_b32_e32 v198, 16, v190
	v_and_b32_e32 v190, 0xffff0000, v190
	v_cvt_pk_bf16_f32 v188, v196, v188
	v_mul_f32_e32 v196, v195, v197
	v_mul_f32_e32 v189, v200, v189
	v_lshlrev_b32_e32 v199, 16, v191
	v_and_b32_e32 v191, 0xffff0000, v191
	v_cvt_pk_bf16_f32 v189, v196, v189
	v_mul_f32_e32 v196, v201, v198
	v_mul_f32_e32 v190, v202, v190
	v_cvt_pk_bf16_f32 v190, v196, v190
	v_mul_f32_e32 v196, v203, v199
	v_mul_f32_e32 v191, v204, v191
	v_cvt_pk_bf16_f32 v191, v196, v191
	ds_read_b128 v[196:199], v176 offset:6976
	v_mfma_f32_16x16x32_bf16 v[56:59], v[20:23], v[4:7], 0
	s_waitcnt lgkmcnt(0)
	v_lshlrev_b32_e32 v205, 16, v198
	v_mfma_f32_16x16x32_bf16 v[60:63], v[20:23], v[0:3], 0
	v_and_b32_e32 v198, 0xffff0000, v198
	v_lshlrev_b32_e32 v206, 16, v199
	v_and_b32_e32 v199, 0xffff0000, v199
	v_mfma_f32_16x16x32_bf16 v[32:35], v[16:19], v[12:15], 0
	v_mfma_f32_16x16x32_bf16 v[36:39], v[16:19], v[8:11], 0
	v_mfma_f32_16x16x32_bf16 v[40:43], v[16:19], v[4:7], 0
	v_mfma_f32_16x16x32_bf16 v[44:47], v[16:19], v[0:3], 0
	v_mfma_f32_16x16x32_bf16 v[16:19], v[28:31], v[12:15], 0
	v_mfma_f32_16x16x32_bf16 v[20:23], v[28:31], v[8:11], 0
	v_mfma_f32_16x16x32_bf16 v[24:27], v[28:31], v[4:7], 0
	v_mfma_f32_16x16x32_bf16 v[28:31], v[28:31], v[0:3], 0
	v_mfma_f32_16x16x32_bf16 v[12:15], v[128:131], v[12:15], 0
	v_mfma_f32_16x16x32_bf16 v[8:11], v[128:131], v[8:11], 0
	v_mfma_f32_16x16x32_bf16 v[4:7], v[128:131], v[4:7], 0
	v_mfma_f32_16x16x32_bf16 v[128:131], v[128:131], v[0:3], 0
	v_lshlrev_b32_e32 v0, 16, v196
	v_and_b32_e32 v1, 0xffff0000, v196
	v_lshlrev_b32_e32 v2, 16, v197
	v_and_b32_e32 v3, 0xffff0000, v197
	v_mul_f32_e32 v0, v192, v0
	v_mul_f32_e32 v1, v193, v1
	v_cvt_pk_bf16_f32 v196, v0, v1
	v_mul_f32_e32 v0, v195, v2
	v_mul_f32_e32 v1, v200, v3
	v_cvt_pk_bf16_f32 v197, v0, v1
	v_mul_f32_e32 v0, v201, v205
	v_mul_f32_e32 v1, v202, v198
	v_cvt_pk_bf16_f32 v198, v0, v1
	v_mul_f32_e32 v0, v203, v206
	v_mul_f32_e32 v1, v204, v199
	v_cvt_pk_bf16_f32 v199, v0, v1
	ds_read_b128 v[0:3], v177 offset:64
	ds_read_b128 v[200:203], v177 offset:2368
	s_waitcnt lgkmcnt(1)
	v_mfma_f32_16x16x32_bf16 v[112:115], v[0:3], v[132:135], v[112:115]
	v_mfma_f32_16x16x32_bf16 v[116:119], v[0:3], v[184:187], v[116:119]
	s_nop 6
	v_cvt_pk_bf16_f32 v112, v112, v113
	v_cvt_pk_bf16_f32 v113, v114, v115
	v_mfma_f32_16x16x32_bf16 v[120:123], v[0:3], v[188:191], v[120:123]
	v_mfma_f32_16x16x32_bf16 v[124:127], v[0:3], v[196:199], v[124:127]
	s_waitcnt lgkmcnt(0)
; __device__ __forceinline__ unsigned cvt_pk_bf16_c(float lo, float hi) { const f32x2_ v = {lo, hi}; return __builtin_bit_cast(unsigned, __builtin_convertvector(v, bf16v2_)); }
; __device__ void phase_ssd1(const Params& p, LAS unsigned char* lds, int wg, int nwg) {
;     ...
;                 for (int pt = 0; pt < 4; ++pt) acc[nt][pt] = __builtin_amdgcn_mfma_f32_16x16x32_bf16(bt, xb[pt], acc[nt][pt], 0, 0, 0);
;             }
;         }
;         bf16_t* sb = S + ((((size_t)b * 128 + c) * 32 + eg) * 64) * 128;
; #pragma unroll
;         for (int pt = 0; pt < 4; ++pt)
; #pragma unroll
;             for (int nt = 0; nt < 8; ++nt) { u32x2 w; w.x = pg8::cvt_pk_bf16_c(acc[nt][pt].x, acc[nt][pt].y); w.y = pg8::cvt_pk_bf16_c(acc[nt][pt].z, acc[nt][pt].w); *(u32x2*)(sb + (size_t)(16 * pt + fr) * 128 + 16 * nt + 4 * fq) = w; }
	v_mfma_f32_16x16x32_bf16 v[96:99], v[200:203], v[132:135], v[96:99]
	v_mfma_f32_16x16x32_bf16 v[100:103], v[200:203], v[184:187], v[100:103]
	v_mfma_f32_16x16x32_bf16 v[104:107], v[200:203], v[188:191], v[104:107]
	s_nop 5
	v_cvt_pk_bf16_f32 v96, v96, v97
	v_cvt_pk_bf16_f32 v97, v98, v99
	v_mfma_f32_16x16x32_bf16 v[108:111], v[200:203], v[196:199], v[108:111]
	ds_read_b128 v[0:3], v177 offset:4672
	ds_read_b128 v[200:203], v177 offset:6976
	s_waitcnt lgkmcnt(1)
	v_mfma_f32_16x16x32_bf16 v[80:83], v[0:3], v[132:135], v[80:83]
	v_mfma_f32_16x16x32_bf16 v[84:87], v[0:3], v[184:187], v[84:87]
	s_nop 6
	v_cvt_pk_bf16_f32 v80, v80, v81
	v_cvt_pk_bf16_f32 v81, v82, v83
	v_mfma_f32_16x16x32_bf16 v[88:91], v[0:3], v[188:191], v[88:91]
	v_mfma_f32_16x16x32_bf16 v[92:95], v[0:3], v[196:199], v[92:95]
	s_waitcnt lgkmcnt(0)
	v_mfma_f32_16x16x32_bf16 v[64:67], v[200:203], v[132:135], v[64:67]
	v_mfma_f32_16x16x32_bf16 v[68:71], v[200:203], v[184:187], v[68:71]
	v_mfma_f32_16x16x32_bf16 v[72:75], v[200:203], v[188:191], v[72:75]
	s_nop 5
	v_cvt_pk_bf16_f32 v64, v64, v65
	v_cvt_pk_bf16_f32 v65, v66, v67
	v_mfma_f32_16x16x32_bf16 v[76:79], v[200:203], v[196:199], v[76:79]
	ds_read_b128 v[0:3], v177 offset:9280
	ds_read_b128 v[200:203], v177 offset:11584
	s_waitcnt lgkmcnt(1)
	v_mfma_f32_16x16x32_bf16 v[48:51], v[0:3], v[132:135], v[48:51]
	v_mfma_f32_16x16x32_bf16 v[52:55], v[0:3], v[184:187], v[52:55]
	s_nop 6
	v_cvt_pk_bf16_f32 v48, v48, v49
	v_cvt_pk_bf16_f32 v49, v50, v51
	v_mfma_f32_16x16x32_bf16 v[56:59], v[0:3], v[188:191], v[56:59]
	v_mfma_f32_16x16x32_bf16 v[60:63], v[0:3], v[196:199], v[60:63]
	s_waitcnt lgkmcnt(0)
	v_mfma_f32_16x16x32_bf16 v[32:35], v[200:203], v[132:135], v[32:35]
	v_mfma_f32_16x16x32_bf16 v[36:39], v[200:203], v[184:187], v[36:39]
	v_mfma_f32_16x16x32_bf16 v[40:43], v[200:203], v[188:191], v[40:43]
	s_nop 5
	v_cvt_pk_bf16_f32 v32, v32, v33
	v_cvt_pk_bf16_f32 v33, v34, v35
	v_mfma_f32_16x16x32_bf16 v[44:47], v[200:203], v[196:199], v[44:47]
	ds_read_b128 v[0:3], v177 offset:13888
	ds_read_b128 v[200:203], v177 offset:16192
	s_waitcnt lgkmcnt(1)
	v_mfma_f32_16x16x32_bf16 v[16:19], v[0:3], v[132:135], v[16:19]
	v_mfma_f32_16x16x32_bf16 v[20:23], v[0:3], v[184:187], v[20:23]
	s_nop 6
	v_cvt_pk_bf16_f32 v16, v16, v17
	v_cvt_pk_bf16_f32 v17, v18, v19
	v_mfma_f32_16x16x32_bf16 v[24:27], v[0:3], v[188:191], v[24:27]
	v_mfma_f32_16x16x32_bf16 v[28:31], v[0:3], v[196:199], v[28:31]
	v_add_u32_e32 v0, s2, v140
	v_ashrrev_i32_e32 v1, 31, v0
	s_waitcnt lgkmcnt(0)
	v_mfma_f32_16x16x32_bf16 v[12:15], v[200:203], v[132:135], v[12:15]
	v_lshlrev_b64 v[132:133], 26, v[138:139]
	v_lshl_add_u64 v[132:133], v[136:137], 0, v[132:133]
	v_mfma_f32_16x16x32_bf16 v[2:5], v[200:203], v[188:191], v[4:7]
	s_nop 2
	v_lshl_add_u64 v[6:7], v[0:1], 0, s[6:7]
	v_lshlrev_b64 v[6:7], 14, v[6:7]
	v_lshl_add_u64 v[6:7], v[132:133], 0, v[6:7]
	v_cvt_pk_bf16_f32 v12, v12, v13
	v_cvt_pk_bf16_f32 v13, v14, v15
	v_add_co_u32_e32 v14, vcc, s27, v6
	v_mfma_f32_16x16x32_bf16 v[8:11], v[200:203], v[184:187], v[8:11]
	s_nop 0
	v_addc_co_u32_e32 v15, vcc, 0, v7, vcc
	s_nop 0
	v_add_co_u32_e32 v248, vcc, s31, v6
	v_cvt_pk_bf16_f32 v2, v2, v3
	s_nop 0
	v_addc_co_u32_e32 v249, vcc, 0, v7, vcc
	v_cvt_pk_bf16_f32 v3, v4, v5
	v_add_co_u32_e32 v244, vcc, s26, v6
	v_cvt_pk_bf16_f32 v8, v8, v9
	v_cvt_pk_bf16_f32 v9, v10, v11
	s_nop 0
	v_cvt_pk_bf16_f32 v124, v124, v125
	v_cvt_pk_bf16_f32 v125, v126, v127
	v_addc_co_u32_e32 v245, vcc, 0, v7, vcc
	s_nop 0
	v_cvt_pk_bf16_f32 v116, v116, v117
	v_cvt_pk_bf16_f32 v117, v118, v119
	s_nop 0
	v_cvt_pk_bf16_f32 v120, v120, v121
	v_cvt_pk_bf16_f32 v121, v122, v123
	s_nop 0
	v_cvt_pk_bf16_f32 v108, v108, v109
	v_cvt_pk_bf16_f32 v109, v110, v111
	s_nop 0
	v_cvt_pk_bf16_f32 v100, v100, v101
	v_cvt_pk_bf16_f32 v101, v102, v103
	s_nop 0
	v_cvt_pk_bf16_f32 v104, v104, v105
	v_cvt_pk_bf16_f32 v105, v106, v107
	s_nop 0
	v_cvt_pk_bf16_f32 v92, v92, v93
	v_cvt_pk_bf16_f32 v93, v94, v95
	v_mfma_f32_16x16x32_bf16 v[128:131], v[200:203], v[196:199], v[128:131]
	v_cvt_pk_bf16_f32 v84, v84, v85
	v_cvt_pk_bf16_f32 v85, v86, v87
	v_cvt_pk_bf16_f32 v88, v88, v89
	v_cvt_pk_bf16_f32 v89, v90, v91
	v_cvt_pk_bf16_f32 v76, v76, v77
	v_cvt_pk_bf16_f32 v77, v78, v79
	v_cvt_pk_bf16_f32 v68, v68, v69
	v_cvt_pk_bf16_f32 v69, v70, v71
	v_cvt_pk_bf16_f32 v72, v72, v73
	v_cvt_pk_bf16_f32 v73, v74, v75
	v_cvt_pk_bf16_f32 v60, v60, v61
	v_cvt_pk_bf16_f32 v61, v62, v63
	v_cvt_pk_bf16_f32 v52, v52, v53
	v_cvt_pk_bf16_f32 v53, v54, v55
	v_cvt_pk_bf16_f32 v56, v56, v57
	v_cvt_pk_bf16_f32 v57, v58, v59
	v_cvt_pk_bf16_f32 v44, v44, v45
	v_cvt_pk_bf16_f32 v45, v46, v47
	v_cvt_pk_bf16_f32 v36, v36, v37
	v_cvt_pk_bf16_f32 v37, v38, v39
	v_cvt_pk_bf16_f32 v40, v40, v41
	v_cvt_pk_bf16_f32 v41, v42, v43
	v_cvt_pk_bf16_f32 v28, v28, v29
	v_cvt_pk_bf16_f32 v29, v30, v31
	v_cvt_pk_bf16_f32 v20, v20, v21
	v_cvt_pk_bf16_f32 v21, v22, v23
	v_cvt_pk_bf16_f32 v24, v24, v25
	v_cvt_pk_bf16_f32 v25, v26, v27
	v_cvt_pk_bf16_f32 v128, v128, v129
	v_cvt_pk_bf16_f32 v129, v130, v131
	s_nop 4
	v_mov_b64_e32 v[246:247], v[14:15]
	s_mov_b32 vcc_lo, 0xffff0000
	s_mov_b32 vcc_hi, 0xffff0000
	v_mov_b32_e32 v250, 24
	s_nop 1
	v_cndmask_b32_e32 v251, 0, v250, vcc
	v_add_co_u32_e64 v6, s[100:101], v6, v251
	v_addc_co_u32_e64 v7, s[100:101], 0, v7, s[100:101]
	v_add_co_u32_e64 v246, s[100:101], v246, v251
	v_addc_co_u32_e64 v247, s[100:101], 0, v247, s[100:101]
	v_add_co_u32_e64 v248, s[100:101], v248, v251
	v_addc_co_u32_e64 v249, s[100:101], 0, v249, s[100:101]
	v_add_co_u32_e64 v244, s[100:101], v244, v251
	v_addc_co_u32_e64 v245, s[100:101], 0, v245, s[100:101]
	v_cndmask_b32_e32 v114, v96, v112, vcc
; __device__ __forceinline__ unsigned cvt_pk_bf16_c(float lo, float hi) { const f32x2_ v = {lo, hi}; return __builtin_bit_cast(unsigned, __builtin_convertvector(v, bf16v2_)); }
; __device__ void phase_ssd1(const Params& p, LAS unsigned char* lds, int wg, int nwg) {
;     ...
;         bf16_t* sb = S + ((((size_t)b * 128 + c) * 32 + eg) * 64) * 128;
; #pragma unroll
;         for (int pt = 0; pt < 4; ++pt)
; #pragma unroll
;             for (int nt = 0; nt < 8; ++nt) { u32x2 w; w.x = pg8::cvt_pk_bf16_c(acc[nt][pt].x, acc[nt][pt].y); w.y = pg8::cvt_pk_bf16_c(acc[nt][pt].z, acc[nt][pt].w); *(u32x2*)(sb + (size_t)(16 * pt + fr) * 128 + 16 * nt + 4 * fq) = w; }
;         if (lane == 0) CD[(b * 128 + c) * 32 + eg] = __expf(alast);
	v_cndmask_b32_e32 v115, v97, v113, vcc
	ds_swizzle_b32 v98, v114 offset:0x401f
	ds_swizzle_b32 v99, v115 offset:0x401f
	v_cndmask_b32_e32 v82, v64, v80, vcc
	v_cndmask_b32_e32 v83, v65, v81, vcc
	ds_swizzle_b32 v66, v82 offset:0x401f
	ds_swizzle_b32 v67, v83 offset:0x401f
	v_cndmask_b32_e32 v50, v32, v48, vcc
	v_cndmask_b32_e32 v51, v33, v49, vcc
	ds_swizzle_b32 v34, v50 offset:0x401f
	ds_swizzle_b32 v35, v51 offset:0x401f
	v_cndmask_b32_e32 v18, v12, v16, vcc
	v_cndmask_b32_e32 v19, v13, v17, vcc
	ds_swizzle_b32 v14, v18 offset:0x401f
	ds_swizzle_b32 v15, v19 offset:0x401f
	v_cndmask_b32_e32 v118, v100, v116, vcc
	v_cndmask_b32_e32 v119, v101, v117, vcc
	ds_swizzle_b32 v102, v118 offset:0x401f
	ds_swizzle_b32 v103, v119 offset:0x401f
	v_cndmask_b32_e32 v86, v68, v84, vcc
	v_cndmask_b32_e32 v87, v69, v85, vcc
	ds_swizzle_b32 v70, v86 offset:0x401f
	ds_swizzle_b32 v71, v87 offset:0x401f
	v_cndmask_b32_e32 v54, v36, v52, vcc
	v_cndmask_b32_e32 v55, v37, v53, vcc
	ds_swizzle_b32 v38, v54 offset:0x401f
	ds_swizzle_b32 v39, v55 offset:0x401f
	v_cndmask_b32_e32 v22, v8, v20, vcc
	v_cndmask_b32_e32 v23, v9, v21, vcc
	ds_swizzle_b32 v10, v22 offset:0x401f
	ds_swizzle_b32 v11, v23 offset:0x401f
	v_cndmask_b32_e32 v122, v104, v120, vcc
	v_cndmask_b32_e32 v123, v105, v121, vcc
	ds_swizzle_b32 v106, v122 offset:0x401f
	ds_swizzle_b32 v107, v123 offset:0x401f
	v_cndmask_b32_e32 v90, v72, v88, vcc
	v_cndmask_b32_e32 v91, v73, v89, vcc
	ds_swizzle_b32 v74, v90 offset:0x401f
	ds_swizzle_b32 v75, v91 offset:0x401f
	v_cndmask_b32_e32 v58, v40, v56, vcc
	v_cndmask_b32_e32 v59, v41, v57, vcc
	ds_swizzle_b32 v42, v58 offset:0x401f
	ds_swizzle_b32 v43, v59 offset:0x401f
	v_cndmask_b32_e32 v26, v2, v24, vcc
	v_cndmask_b32_e32 v27, v3, v25, vcc
	ds_swizzle_b32 v4, v26 offset:0x401f
	ds_swizzle_b32 v5, v27 offset:0x401f
	v_cndmask_b32_e32 v126, v108, v124, vcc
	v_cndmask_b32_e32 v127, v109, v125, vcc
	ds_swizzle_b32 v110, v126 offset:0x401f
	ds_swizzle_b32 v111, v127 offset:0x401f
	v_cndmask_b32_e32 v94, v76, v92, vcc
	v_cndmask_b32_e32 v95, v77, v93, vcc
	ds_swizzle_b32 v78, v94 offset:0x401f
	ds_swizzle_b32 v79, v95 offset:0x401f
	v_cndmask_b32_e32 v62, v44, v60, vcc
	v_cndmask_b32_e32 v63, v45, v61, vcc
	ds_swizzle_b32 v46, v62 offset:0x401f
	ds_swizzle_b32 v47, v63 offset:0x401f
	v_cndmask_b32_e32 v30, v128, v28, vcc
	v_cndmask_b32_e32 v31, v129, v29, vcc
	ds_swizzle_b32 v130, v30 offset:0x401f
	ds_swizzle_b32 v131, v31 offset:0x401f
	s_waitcnt lgkmcnt(0)
	v_cndmask_b32_e32 v114, v98, v96, vcc
	v_cndmask_b32_e32 v115, v99, v97, vcc
	v_cndmask_b32_e32 v112, v112, v98, vcc
	v_cndmask_b32_e32 v113, v113, v99, vcc
	global_store_dwordx4 v[6:7], v[112:115], off
	v_cndmask_b32_e32 v82, v66, v64, vcc
	v_cndmask_b32_e32 v83, v67, v65, vcc
	v_cndmask_b32_e32 v80, v80, v66, vcc
	v_cndmask_b32_e32 v81, v81, v67, vcc
	global_store_dwordx4 v[6:7], v[80:83], off offset:64
	v_cndmask_b32_e32 v50, v34, v32, vcc
	v_cndmask_b32_e32 v51, v35, v33, vcc
	v_cndmask_b32_e32 v48, v48, v34, vcc
	v_cndmask_b32_e32 v49, v49, v35, vcc
	global_store_dwordx4 v[6:7], v[48:51], off offset:128
	v_cndmask_b32_e32 v18, v14, v12, vcc
	v_cndmask_b32_e32 v19, v15, v13, vcc
	v_cndmask_b32_e32 v16, v16, v14, vcc
	v_cndmask_b32_e32 v17, v17, v15, vcc
	global_store_dwordx4 v[6:7], v[16:19], off offset:192
	v_cndmask_b32_e32 v118, v102, v100, vcc
	v_cndmask_b32_e32 v119, v103, v101, vcc
	v_cndmask_b32_e32 v116, v116, v102, vcc
	v_cndmask_b32_e32 v117, v117, v103, vcc
	global_store_dwordx4 v[246:247], v[116:119], off
	v_cndmask_b32_e32 v86, v70, v68, vcc
	v_cndmask_b32_e32 v87, v71, v69, vcc
	v_cndmask_b32_e32 v84, v84, v70, vcc
	v_cndmask_b32_e32 v85, v85, v71, vcc
	global_store_dwordx4 v[246:247], v[84:87], off offset:64
	v_cndmask_b32_e32 v54, v38, v36, vcc
	v_cndmask_b32_e32 v55, v39, v37, vcc
	v_cndmask_b32_e32 v52, v52, v38, vcc
	v_cndmask_b32_e32 v53, v53, v39, vcc
	global_store_dwordx4 v[246:247], v[52:55], off offset:128
	v_cndmask_b32_e32 v22, v10, v8, vcc
	v_cndmask_b32_e32 v23, v11, v9, vcc
	v_cndmask_b32_e32 v20, v20, v10, vcc
	v_cndmask_b32_e32 v21, v21, v11, vcc
	global_store_dwordx4 v[246:247], v[20:23], off offset:192
	v_cndmask_b32_e32 v122, v106, v104, vcc
	v_cndmask_b32_e32 v123, v107, v105, vcc
	v_cndmask_b32_e32 v120, v120, v106, vcc
	v_cndmask_b32_e32 v121, v121, v107, vcc
	global_store_dwordx4 v[248:249], v[120:123], off
	v_cndmask_b32_e32 v90, v74, v72, vcc
	v_cndmask_b32_e32 v91, v75, v73, vcc
	v_cndmask_b32_e32 v88, v88, v74, vcc
	v_cndmask_b32_e32 v89, v89, v75, vcc
	global_store_dwordx4 v[248:249], v[88:91], off offset:64
	v_cndmask_b32_e32 v58, v42, v40, vcc
	v_cndmask_b32_e32 v59, v43, v41, vcc
	v_cndmask_b32_e32 v56, v56, v42, vcc
	v_cndmask_b32_e32 v57, v57, v43, vcc
	global_store_dwordx4 v[248:249], v[56:59], off offset:128
	v_cndmask_b32_e32 v26, v4, v2, vcc
	v_cndmask_b32_e32 v27, v5, v3, vcc
	v_cndmask_b32_e32 v24, v24, v4, vcc
	v_cndmask_b32_e32 v25, v25, v5, vcc
	global_store_dwordx4 v[248:249], v[24:27], off offset:192
	v_cndmask_b32_e32 v126, v110, v108, vcc
	v_cndmask_b32_e32 v127, v111, v109, vcc
	v_cndmask_b32_e32 v124, v124, v110, vcc
	v_cndmask_b32_e32 v125, v125, v111, vcc
	global_store_dwordx4 v[244:245], v[124:127], off
	v_cndmask_b32_e32 v94, v78, v76, vcc
	v_cndmask_b32_e32 v95, v79, v77, vcc
	v_cndmask_b32_e32 v92, v92, v78, vcc
	v_cndmask_b32_e32 v93, v93, v79, vcc
	global_store_dwordx4 v[244:245], v[92:95], off offset:64
	v_cndmask_b32_e32 v62, v46, v44, vcc
	v_cndmask_b32_e32 v63, v47, v45, vcc
	v_cndmask_b32_e32 v60, v60, v46, vcc
	v_cndmask_b32_e32 v61, v61, v47, vcc
	global_store_dwordx4 v[244:245], v[60:63], off offset:128
	v_cndmask_b32_e32 v30, v130, v128, vcc
	v_cndmask_b32_e32 v31, v131, v129, vcc
	v_cndmask_b32_e32 v28, v28, v130, vcc
	v_cndmask_b32_e32 v29, v29, v131, vcc
	global_store_dwordx4 v[244:245], v[28:31], off offset:192
	s_and_saveexec_b64 s[2:3], s[0:1]
	s_cbranch_execz .LBB0_551
	v_mul_f32_e32 v1, 0x3fb8aa3b, v183
	s_lshl_b32 s4, s18, 12
	v_exp_f32_e32 v2, v1
	s_or_b32 s4, s6, s4
	v_add_u32_e32 v0, s4, v0
	v_readlane_b32 s4, v253, 54
	v_ashrrev_i32_e32 v1, 31, v0
	v_readlane_b32 s5, v253, 55
	s_nop 1
	v_lshl_add_u64 v[0:1], v[0:1], 2, s[4:5]
	global_store_dword v[0:1], v2, off
	s_branch .LBB0_551
